# means batched loads + MODE0 sink scalar load + LN slot/gamma hoists (no LN residual warming)
# speedup vs baseline: 1.0028x; 1.0028x over previous
.LBB0_251:
	v_lshl_add_u64 v[16:17], v[6:7], 0, s[8:9]
	v_add_co_u32_e32 v18, vcc, 0xf600000, v16
	s_nop 1
	v_addc_co_u32_e32 v19, vcc, 0, v17, vcc
	v_add_co_u32_e32 v20, vcc, 0xf60c000, v16
	s_nop 1
	v_addc_co_u32_e32 v21, vcc, 0, v17, vcc
	v_add_co_u32_e32 v42, vcc, 0xf618000, v16
	s_nop 1
	v_addc_co_u32_e32 v43, vcc, 0, v17, vcc
	v_add_co_u32_e32 v44, vcc, 0xf624000, v16
	s_nop 1
	v_addc_co_u32_e32 v45, vcc, 0, v17, vcc
	global_load_dwordx4 v[26:29], v[18:19], off offset:2048
	global_load_dwordx4 v[30:33], v[20:21], off offset:2048
	global_load_dwordx4 v[34:37], v[42:43], off offset:2048
	global_load_dwordx4 v[38:41], v[44:45], off offset:2048
	s_add_u32 s8, s8, 0x30000
	s_addc_u32 s9, s9, 0
	s_waitcnt vmcnt(3)
	v_lshlrev_b32_e32 v24, 16, v26
	v_and_b32_e32 v25, 0xffff0000, v26
	v_pk_add_f32 v[14:15], v[14:15], v[24:25]
	v_lshlrev_b32_e32 v24, 16, v27
	v_and_b32_e32 v25, 0xffff0000, v27
	v_pk_add_f32 v[12:13], v[12:13], v[24:25]
	v_lshlrev_b32_e32 v24, 16, v28
	v_and_b32_e32 v25, 0xffff0000, v28
	v_pk_add_f32 v[10:11], v[10:11], v[24:25]
	v_lshlrev_b32_e32 v24, 16, v29
	v_and_b32_e32 v25, 0xffff0000, v29
	v_pk_add_f32 v[8:9], v[8:9], v[24:25]
	s_waitcnt vmcnt(2)
	v_lshlrev_b32_e32 v24, 16, v30
	v_and_b32_e32 v25, 0xffff0000, v30
	v_pk_add_f32 v[14:15], v[14:15], v[24:25]
	v_lshlrev_b32_e32 v24, 16, v31
	v_and_b32_e32 v25, 0xffff0000, v31
	v_pk_add_f32 v[12:13], v[12:13], v[24:25]
	v_lshlrev_b32_e32 v24, 16, v32
	v_and_b32_e32 v25, 0xffff0000, v32
	v_pk_add_f32 v[10:11], v[10:11], v[24:25]
	v_lshlrev_b32_e32 v24, 16, v33
	v_and_b32_e32 v25, 0xffff0000, v33
	v_pk_add_f32 v[8:9], v[8:9], v[24:25]
	s_waitcnt vmcnt(1)
	v_lshlrev_b32_e32 v24, 16, v34
	v_and_b32_e32 v25, 0xffff0000, v34
	v_pk_add_f32 v[14:15], v[14:15], v[24:25]
	v_lshlrev_b32_e32 v24, 16, v35
	v_and_b32_e32 v25, 0xffff0000, v35
	v_pk_add_f32 v[12:13], v[12:13], v[24:25]
	v_lshlrev_b32_e32 v24, 16, v36
	v_and_b32_e32 v25, 0xffff0000, v36
	v_pk_add_f32 v[10:11], v[10:11], v[24:25]
	v_lshlrev_b32_e32 v24, 16, v37
	v_and_b32_e32 v25, 0xffff0000, v37
	v_pk_add_f32 v[8:9], v[8:9], v[24:25]
	s_waitcnt vmcnt(0)
	v_lshlrev_b32_e32 v24, 16, v38
	v_and_b32_e32 v25, 0xffff0000, v38
	v_pk_add_f32 v[14:15], v[14:15], v[24:25]
	v_lshlrev_b32_e32 v24, 16, v39
	v_and_b32_e32 v25, 0xffff0000, v39
	v_pk_add_f32 v[12:13], v[12:13], v[24:25]
	v_lshlrev_b32_e32 v24, 16, v40
	v_and_b32_e32 v25, 0xffff0000, v40
	v_pk_add_f32 v[10:11], v[10:11], v[24:25]
	v_lshlrev_b32_e32 v24, 16, v41
	v_and_b32_e32 v25, 0xffff0000, v41
	v_pk_add_f32 v[8:9], v[8:9], v[24:25]
	s_cmp_lg_u32 s8, 0x180000
	s_cbranch_scc1 .LBB0_251
	ds_bpermute_b32 v6, v1, v14
	ds_bpermute_b32 v7, v1, v15
	ds_bpermute_b32 v16, v1, v12
	ds_bpermute_b32 v17, v1, v13
	ds_bpermute_b32 v20, v1, v10
	ds_bpermute_b32 v21, v1, v11
	s_waitcnt lgkmcnt(4)
	v_pk_add_f32 v[6:7], v[14:15], v[6:7]
	ds_bpermute_b32 v14, v22, v6
	s_waitcnt lgkmcnt(3)
	v_pk_add_f32 v[16:17], v[12:13], v[16:17]
	ds_bpermute_b32 v15, v22, v7
	ds_bpermute_b32 v18, v22, v16
	ds_bpermute_b32 v19, v22, v17
	s_waitcnt lgkmcnt(4)
	v_pk_add_f32 v[10:11], v[10:11], v[20:21]
	ds_bpermute_b32 v20, v22, v10
	s_waitcnt lgkmcnt(3)
	v_pk_add_f32 v[6:7], v[6:7], v[14:15]
	ds_bpermute_b32 v21, v22, v11
	s_waitcnt lgkmcnt(2)
	v_pk_add_f32 v[14:15], v[16:17], v[18:19]
	ds_bpermute_b32 v18, v1, v8
	ds_bpermute_b32 v19, v1, v9
	ds_bpermute_b32 v12, v23, v6
	ds_bpermute_b32 v13, v23, v7
	ds_bpermute_b32 v16, v23, v14
	ds_bpermute_b32 v17, v23, v15
	s_waitcnt lgkmcnt(4)
	v_pk_add_f32 v[18:19], v[8:9], v[18:19]
	ds_bpermute_b32 v24, v22, v18
	ds_bpermute_b32 v25, v22, v19
	v_pk_add_f32 v[8:9], v[10:11], v[20:21]
	ds_bpermute_b32 v10, v23, v8
	ds_bpermute_b32 v11, v23, v9
	s_waitcnt lgkmcnt(2)
	v_pk_add_f32 v[18:19], v[18:19], v[24:25]
	ds_bpermute_b32 v20, v23, v18
	ds_bpermute_b32 v21, v23, v19
	s_and_saveexec_b64 s[8:9], s[4:5]
	v_readlane_b32 s14, v253, 49
	v_readlane_b32 s15, v253, 50
	s_cbranch_execz .LBB0_249
	s_ashr_i32 s7, s6, 31
	s_lshl_b64 s[12:13], s[6:7], 8
	v_lshl_add_u64 v[24:25], v[2:3], 0, s[12:13]
	v_pk_add_f32 v[6:7], v[6:7], v[12:13]
	s_mov_b32 s12, 0x3b800000
	v_pk_mul_f32 v[12:13], v[6:7], s[12:13] op_sel_hi:[1,0]
	v_pk_add_f32 v[6:7], v[14:15], v[16:17]
	s_nop 0
	v_pk_mul_f32 v[14:15], v[6:7], s[12:13] op_sel_hi:[1,0]
	s_waitcnt lgkmcnt(2)
	v_pk_add_f32 v[6:7], v[8:9], v[10:11]
	s_waitcnt lgkmcnt(0)
	v_pk_add_f32 v[8:9], v[18:19], v[20:21]
	v_pk_mul_f32 v[6:7], v[6:7], s[12:13] op_sel_hi:[1,0]
	v_pk_mul_f32 v[8:9], v[8:9], s[12:13] op_sel_hi:[1,0]
	global_store_dwordx4 v[24:25], v[12:15], off
	global_store_dwordx4 v[24:25], v[6:9], off offset:16
	s_branch .LBB0_249

.LBB0_454:
	s_andn2_b64 vcc, exec, s[4:5]
	s_cbranch_vccnz .LBB0_327
	s_and_b32 s4, s99, 56
	v_mov_b32_e32 v3, v237
	v_writelane_b32 v255, s99, 49
	s_add_i32 s74, s4, -2
	s_sub_i32 s75, 3, s4
	s_sub_i32 s76, 2, s4
	v_readlane_b32 s16, v255, 43
	v_readfirstlane_b32 s4, v3
	s_ashr_i32 s10, s4, 6
	s_lshl_b32 s5, s16, 3
	s_ashr_i32 s6, s16, 5
	s_ashr_i32 s13, s4, 7
	s_lshl_b32 s4, s10, 5
	s_lshl_b32 s11, s10, 9
	s_bfe_u32 s12, s16, 0x20003
	v_writelane_b32 v255, s5, 50
	s_and_b32 s17, s5, 56
	s_and_b32 s77, s4, 32
	s_ashr_i32 s7, s6, 31
	s_mul_i32 s5, s6, 0xc00000
	s_mul_hi_i32 s4, s6, 0xc00000
	s_add_u32 s14, s96, s5
	s_addc_u32 s15, s97, s4
	s_lshl_b32 s4, s12, 7
	v_ashrrev_i32_e32 v8, 3, v3
	s_add_u32 s4, s14, s4
	s_movk_i32 s8, 0x600
	v_lshlrev_b32_e32 v0, 10, v3
	s_addc_u32 s5, s15, 0
	v_mad_i64_i32 v[158:159], s[8:9], v8, s8, 0
	v_and_b32_e32 v9, 7, v3
	s_waitcnt lgkmcnt(0)
	v_and_b32_e32 v10, 0x1000, v0
	v_lshl_add_u64 v[0:1], v[158:159], 1, s[4:5]
	s_max_u32 s4, s17, 2
	v_lshlrev_b32_e32 v192, 4, v9
	s_lshl_b32 s4, s4, 6
	v_lshl_add_u64 v[0:1], v[0:1], 0, v[192:193]
	s_addk_i32 s4, 0xff80
	v_mad_u64_u32 v[4:5], s[4:5], s4, v230, v[0:1]
	s_max_u32 s4, s17, 1
	s_lshl_b32 s4, s4, 6
	s_sub_i32 s4, s4, 64
	global_load_dwordx4 v[98:101], v[4:5], off offset:2048
	global_load_dwordx4 v[102:105], v[4:5], off offset:2560
	v_mad_u64_u32 v[4:5], s[4:5], s4, v230, v[0:1]
	s_lshl_b32 s4, s17, 6
	s_or_b32 s8, s77, s4
	s_lshl_b32 s4, s12, 8
	s_lshl_b32 s5, s13, 6
	s_mul_i32 s80, s17, 0x30000
	s_add_i32 s4, s5, s4
	v_and_b32_e32 v168, 31, v3
	v_lshl_add_u64 v[0:1], v[0:1], 0, s[80:81]
	v_writelane_b32 v255, s5, 51
	s_ashr_i32 s5, s4, 31
	global_load_dwordx4 v[106:109], v[4:5], off offset:2048
	global_load_dwordx4 v[110:113], v[4:5], off offset:2560
	global_load_dwordx4 v[114:117], v[0:1], off offset:2048
	global_load_dwordx4 v[118:121], v[0:1], off offset:2560
	s_lshl_b64 s[4:5], s[4:5], 1
	v_or_b32_e32 v0, s8, v168
	s_add_u32 s4, s14, s4
	v_mul_u32_u24_e32 v0, 0x600, v0
	v_bfe_u32 v7, v3, 5, 1
	s_addc_u32 s5, s15, s5
	v_lshlrev_b32_e32 v192, 1, v0
	v_lshl_add_u64 v[0:1], s[4:5], 0, v[192:193]
	v_lshlrev_b32_e32 v160, 4, v7
	v_mov_b32_e32 v161, v193
	v_lshl_add_u64 v[0:1], v[0:1], 0, v[160:161]
	global_load_dwordx4 v[150:153], v[0:1], off
	global_load_dwordx4 v[146:149], v[0:1], off offset:32
	global_load_dwordx4 v[142:145], v[0:1], off offset:64
	global_load_dwordx4 v[138:141], v[0:1], off offset:96
	s_lshr_b32 s4, s16, 1
	s_add_i32 s99, s11, 0
	s_and_b32 s4, s4, 12
	s_add_i32 s99, s99, 0x18300
	s_add_i32 s8, s13, s4
	s_lshl_b64 s[6:7], s[6:7], 23
	v_readlane_b32 s9, v253, 54
	s_add_u32 s9, s9, s6
	v_readlane_b32 s6, v253, 55
	s_addc_u32 s11, s6, s7
	s_lshl_b32 s6, s8, 6
	s_ashr_i32 s7, s6, 31
	s_lshl_b64 s[6:7], s[6:7], 1
	s_add_u32 s6, s9, s6
	s_addc_u32 s7, s11, s7
	s_ashr_i32 s9, s8, 31
	s_waitcnt lgkmcnt(2)
	v_lshlrev_b32_e32 v11, 4, v3
	s_movk_i32 s5, 0x410
	s_lshl_b64 s[8:9], s[8:9], 2
	v_readlane_b32 s11, v255, 26
	v_and_b32_e32 v12, 48, v11
	v_lshlrev_b32_e32 v2, 3, v9
	v_lshlrev_b32_e32 v5, 4, v8
	v_lshlrev_b32_e32 v0, 6, v8
	v_mad_u32_u24 v8, v9, s5, 0
	v_add_u32_e32 v9, 0, v10
	s_add_u32 s12, s11, s8
	v_readlane_b32 s8, v255, 27
	v_bfe_u32 v175, v3, 3, 3
	v_and_b32_e32 v6, 63, v3
	v_lshlrev_b32_e32 v13, 4, v168
	v_add3_u32 v161, v9, v0, v12
	s_addc_u32 s13, s8, s9
	s_lshl_b32 s8, s10, 12
	v_and_b32_e32 v0, 4, v175
	v_mad_u32_u24 v170, v7, s5, v13
	v_cmp_gt_u32_e64 s[4:5], 32, v6
	v_lshl_add_u32 v174, v6, 2, s99
	s_add_i32 s8, s8, 0
	v_lshl_add_u32 v176, v0, 2, s99
	v_lshlrev_b32_e32 v0, 7, v0
	v_lshlrev_b32_e32 v6, 1, v6
	s_add_i32 s8, s8, 0x19300
	v_or3_b32 v9, v0, v6, 64
	v_lshlrev_b32_e32 v14, 1, v3
	v_lshlrev_b32_e32 v15, 3, v3
	v_lshl_add_u32 v3, v168, 1, s8
	v_add_u32_e32 v178, s8, v9
	v_or_b32_e32 v9, 0x80, v0
	v_add_u32_e32 v179, v3, v9
	v_or3_b32 v9, v9, v6, 64
	v_add_u32_e32 v180, s8, v9
	v_or_b32_e32 v9, 0x100, v0
	v_add_u32_e32 v181, v3, v9
	v_or3_b32 v9, v9, v6, 64
	v_add_u32_e32 v182, s8, v9
	v_or_b32_e32 v9, 3, v175
	v_lshl_add_u32 v183, v9, 2, s99
	v_lshlrev_b32_e32 v9, 7, v9
	v_add_u32_e32 v184, v3, v9
	v_or3_b32 v9, v9, v6, 64
	v_add_u32_e32 v185, s8, v9
	v_or_b32_e32 v9, 0x400, v0
	v_add_u32_e32 v186, v3, v9
	v_or3_b32 v9, v9, v6, 64
	v_add_u32_e32 v187, s8, v9
	v_or_b32_e32 v9, 0x480, v0
	v_add_u32_e32 v188, v3, v9
	v_or3_b32 v9, v9, v6, 64
	v_add_u32_e32 v189, s8, v9
	v_or_b32_e32 v9, 0x500, v0
	v_add_u32_e32 v190, v3, v9
	v_or3_b32 v9, v9, v6, 64
	v_add_u32_e32 v191, s8, v9
	v_or_b32_e32 v9, 11, v175
	v_lshl_add_u32 v196, v9, 2, s99
	v_lshlrev_b32_e32 v9, 7, v9
	v_add_u32_e32 v197, v3, v9
	v_or3_b32 v9, v9, v6, 64
	v_add_u32_e32 v198, s8, v9
	v_or_b32_e32 v9, 0x800, v0
	v_add_u32_e32 v199, v3, v9
	v_or3_b32 v9, v9, v6, 64
	v_add_u32_e32 v200, s8, v9
	v_or_b32_e32 v9, 0x880, v0
	v_add_u32_e32 v201, v3, v9
	v_or3_b32 v9, v9, v6, 64
	v_add_u32_e32 v202, s8, v9
	v_or_b32_e32 v9, 0x900, v0
	v_add_u32_e32 v203, v3, v9
	v_or3_b32 v9, v9, v6, 64
	v_add_u32_e32 v204, s8, v9
	v_or_b32_e32 v9, 19, v175
	v_lshl_add_u32 v205, v9, 2, s99
	v_lshlrev_b32_e32 v9, 7, v9
	v_add_u32_e32 v206, v3, v9
	v_or3_b32 v9, v9, v6, 64
	v_add_u32_e32 v207, s8, v9
	v_or_b32_e32 v9, 0xc00, v0
	v_add_u32_e32 v208, v3, v9
	v_or3_b32 v9, v9, v6, 64
	v_add_u32_e32 v177, v3, v0
	v_add_u32_e32 v209, s8, v9
	v_or_b32_e32 v9, 0xc80, v0
	v_or_b32_e32 v0, 0xd00, v0
	v_add_u32_e32 v212, v3, v0
	v_or3_b32 v0, v0, v6, 64
	v_add_u32_e32 v213, s8, v0
	v_or_b32_e32 v0, 27, v175
	v_lshl_add_u32 v214, v0, 2, s99
	v_lshlrev_b32_e32 v0, 7, v0
	v_and_b32_e32 v16, 0xc0, v11
	v_writelane_b32 v255, s12, 52
	v_add_u32_e32 v210, v3, v9
	v_or3_b32 v9, v9, v6, 64
	v_add_u32_e32 v215, v3, v0
	v_or3_b32 v0, v0, v6, 64
	v_and_b32_e32 v192, 0x70, v11
	v_or_b32_e32 v217, 8, v175
	v_or_b32_e32 v218, 16, v175
	v_or_b32_e32 v219, 24, v175
	v_and_b32_e32 v14, 32, v14
	v_lshlrev_b32_e32 v4, 3, v7
	v_and_b32_e32 v1, 24, v15
	v_lshlrev_b32_e32 v172, 2, v7
	v_writelane_b32 v255, s13, 53
	s_load_dword s12, s[12:13], 0x0
	s_waitcnt lgkmcnt(0)
	s_nop 0
	v_writelane_b32 v255, s12, 55
	v_add_u32_e32 v211, s8, v9
	v_add_u32_e32 v216, s8, v0
	v_add_u32_e32 v0, s8, v192
	v_lshlrev_b32_e32 v3, 7, v175
	v_lshlrev_b32_e32 v6, 7, v217
	v_lshlrev_b32_e32 v9, 7, v218
	v_lshlrev_b32_e32 v10, 7, v219
	v_lshl_or_b32 v7, v7, 8, v16
	s_waitcnt vmcnt(0)
	v_mov_b64_e32 v[122:123], v[138:139]
	v_mov_b64_e32 v[126:127], v[142:143]
	v_mov_b64_e32 v[130:131], v[146:147]
	v_mov_b64_e32 v[134:135], v[150:151]
	v_add_u32_e32 v169, 0xc300, v161
	v_add_u32_e32 v171, 0, v170
	v_lshl_add_u32 v173, v168, 2, s99
	v_lshl_add_u64 v[162:163], s[6:7], 0, v[192:193]
	v_or_b32_e32 v220, s77, v168
	v_or3_b32 v221, v7, v14, v1
	s_mov_b32 s6, 0
	v_add_u32_e32 v222, v8, v5
	v_lshlrev_b32_e32 v164, 1, v2
	v_lshlrev_b32_e32 v166, 1, v4
	v_add_u32_e32 v223, v0, v3
	v_add_u32_e32 v232, v0, v6
	v_add_u32_e32 v233, v0, v9
	v_add_u32_e32 v234, v0, v10
	v_mov_b64_e32 v[124:125], v[140:141]
	v_mov_b64_e32 v[128:129], v[144:145]
	v_mov_b64_e32 v[132:133], v[148:149]
	v_mov_b64_e32 v[136:137], v[152:153]
	v_writelane_b32 v255, s17, 54
	s_branch .LBB0_457

.LBB0_490:
	v_mov_b32_e32 v32, v165
	s_nop 1
	v_permlane32_swap_b32_e32 v165, v32
	s_and_saveexec_b64 s[6:7], s[4:5]
	s_cbranch_execz .LBB0_456
	v_readlane_b32 s9, v255, 55
	v_add_f32_e32 v32, v165, v32
	s_mov_b32 s8, 0x3fb8aa3b
	v_mov_b32_e32 v33, s9
	v_fma_f32 v33, v33, s8, -v64
	v_exp_f32_e32 v33, v33
	s_nop 0
	v_add_f32_e32 v32, v32, v33
	v_rcp_f32_e32 v33, v32
	v_log_f32_e32 v32, v32
	ds_write_b32 v173, v33
	v_add_f32_e32 v32, v64, v32
	ds_write_b32 v174, v32 offset:128
	s_branch .LBB0_456

.LBB0_714:
	s_or_b64 exec, exec, s[12:13]
	v_lshlrev_b64 v[160:161], 2, v[186:187]
	v_lshl_add_u64 v[162:163], s[30:31], 0, v[160:161]
	v_lshl_add_u64 v[160:161], s[34:35], 0, v[160:161]
	global_load_dwordx4 v[144:147], v[162:163], off offset:16
	global_load_dwordx4 v[152:155], v[162:163], off
	global_load_dwordx4 v[148:151], v[160:161], off offset:16
	global_load_dwordx4 v[156:159], v[160:161], off
	s_andn2_b64 vcc, exec, s[38:39]
	s_cbranch_vccnz .LBB0_720
	s_lshl_b32 s12, s78, 6
	s_ashr_i32 s13, s12, 31
	s_lshl_b64 s[12:13], s[12:13], 2
	s_add_u32 s12, s67, s12
	s_addc_u32 s13, s68, s13
	s_waitcnt lgkmcnt(0)
	v_mov_b32_e32 v130, 0x1000000
	s_branch .LBB0_717

.LBB0_720:
	s_waitcnt vmcnt(0) lgkmcnt(0)
	s_barrier
	s_and_saveexec_b64 s[50:51], s[6:7]
	s_cbranch_execz .LBB0_722
	v_readlane_b32 s12, v253, 62
	v_lshlrev_b64 v[128:129], 5, v[128:129]
	v_readlane_b32 s13, v253, 63
	s_nop 1
	v_lshl_add_u64 v[128:129], s[12:13], 0, v[128:129]
	s_waitcnt lgkmcnt(0)
	global_load_dwordx2 v[130:131], v[128:129], off sc1
	global_load_dwordx2 v[132:133], v[128:129], off offset:8 sc1
	global_load_dwordx2 v[140:141], v[128:129], off offset:16 sc1
	global_load_dwordx2 v[142:143], v[128:129], off offset:24 sc1
	s_mov_b32 s12, 0xf800000
	s_waitcnt vmcnt(3)
	v_add_f32_e32 v134, 0, v130
	s_waitcnt vmcnt(2)
	v_add_f32_e32 v136, v134, v132
	s_waitcnt vmcnt(1)
	v_mov_b32_e32 v134, v140
	v_mov_b32_e32 v135, v141
	v_add_f32_e32 v136, v136, v134
	s_waitcnt vmcnt(0)
	v_mov_b32_e32 v128, v142
	v_mov_b32_e32 v129, v143
	v_add_f32_e32 v137, v136, v128
	v_fmamk_f32 v130, v137, 0xbe800000, v130
	v_mul_f32_e32 v138, 0x43800000, v130
	v_fmac_f32_e32 v131, v130, v138
	v_add_f32_e32 v130, 0, v131
	v_fmamk_f32 v131, v137, 0xbe800000, v132
	v_mul_f32_e32 v132, 0x43800000, v131
	v_fmac_f32_e32 v133, v131, v132
	v_fmamk_f32 v131, v137, 0xbe800000, v134
	v_mul_f32_e32 v132, 0x43800000, v131
	v_fmamk_f32 v128, v137, 0xbe800000, v128
	v_add_f32_e32 v130, v133, v130
	v_fmac_f32_e32 v135, v131, v132
	v_mul_f32_e32 v131, 0x43800000, v128
	v_add_f32_e32 v130, v135, v130
	v_fmac_f32_e32 v129, v128, v131
	v_add_f32_e32 v128, v129, v130
	v_mov_b32_e32 v129, 0x3727c5ac
	v_fmamk_f32 v128, v128, 0x3a800000, v129
	v_cmp_gt_f32_e32 vcc, s12, v128
	v_mul_f32_e32 v129, 0x4f800000, v128
	v_mul_f32_e32 v136, 0x3e800000, v137
	v_cndmask_b32_e32 v128, v128, v129, vcc
	v_sqrt_f32_e32 v129, v128
	s_nop 0
	v_add_u32_e32 v130, -1, v129
	v_fma_f32 v131, -v130, v129, v128
	v_cmp_ge_f32_e64 s[12:13], 0, v131
	v_add_u32_e32 v131, 1, v129
	s_nop 0
	v_cndmask_b32_e64 v130, v129, v130, s[12:13]
	v_fma_f32 v129, -v131, v129, v128
	v_cmp_lt_f32_e64 s[12:13], 0, v129
	s_nop 1
	v_cndmask_b32_e64 v129, v130, v131, s[12:13]
	v_mul_f32_e32 v130, 0x37800000, v129
	v_cndmask_b32_e32 v129, v129, v130, vcc
	v_mov_b32_e32 v130, 0x260
	v_cmp_class_f32_e32 vcc, v128, v130
	s_nop 1
	v_cndmask_b32_e32 v128, v129, v128, vcc
	v_div_scale_f32 v129, s[12:13], v128, v128, 1.0
	v_rcp_f32_e32 v130, v129
	s_nop 0
	v_fma_f32 v131, -v129, v130, 1.0
	v_fmac_f32_e32 v130, v131, v130
	v_div_scale_f32 v131, vcc, 1.0, v128, 1.0
	v_mul_f32_e32 v132, v131, v130
	v_fma_f32 v133, -v129, v132, v131
	v_fmac_f32_e32 v132, v133, v130
	v_fma_f32 v129, -v129, v132, v131
	v_div_fmas_f32 v129, v129, v130, v132
	v_div_fixup_f32 v137, v129, v128, 1.0
	ds_write_b64 v208, v[136:137]
.LBB0_722:
	s_or_b64 exec, exec, s[50:51]
	v_lshlrev_b64 v[128:129], 2, v[186:187]
	s_waitcnt lgkmcnt(0)
	s_barrier
	v_lshl_add_u64 v[132:133], s[30:31], 0, v[128:129]
	v_lshl_add_u64 v[140:141], s[34:35], 0, v[128:129]
	s_waitcnt lgkmcnt(0)
	global_load_dwordx4 v[128:131], v[132:133], off offset:528
	global_load_dwordx4 v[136:139], v[132:133], off offset:512
	s_nop 0
	global_load_dwordx4 v[132:135], v[140:141], off offset:528
	s_nop 0
	global_load_dwordx4 v[140:143], v[140:141], off offset:512
	ds_read_b64 v[160:161], v209
	v_lshlrev_b64 v[162:163], 10, v[188:189]
	v_lshl_add_u64 v[162:163], v[162:163], 0, v[186:187]
	s_and_b64 vcc, exec, s[44:45]
	v_lshl_add_u64 v[164:165], v[162:163], 2, s[28:29]
	s_waitcnt lgkmcnt(0)
	v_sub_f32_e32 v75, v75, v160
	v_sub_f32_e32 v74, v74, v160
	v_sub_f32_e32 v73, v73, v160
	v_sub_f32_e32 v72, v72, v160
	v_sub_f32_e32 v71, v71, v160
	v_sub_f32_e32 v70, v70, v160
	v_sub_f32_e32 v69, v69, v160
	v_sub_f32_e32 v68, v68, v160
	v_pk_mul_f32 v[72:73], v[160:161], v[72:73] op_sel:[1,0]
	v_pk_mul_f32 v[74:75], v[160:161], v[74:75] op_sel:[1,0]
	v_pk_mul_f32 v[68:69], v[160:161], v[68:69] op_sel:[1,0]
	v_pk_mul_f32 v[70:71], v[160:161], v[70:71] op_sel:[1,0]
	s_waitcnt vmcnt(5)
	v_pk_fma_f32 v[68:69], v[144:145], v[68:69], v[148:149]
	s_waitcnt vmcnt(4)
	v_pk_fma_f32 v[74:75], v[154:155], v[74:75], v[158:159]
	v_pk_fma_f32 v[72:73], v[152:153], v[72:73], v[156:157]
	v_pk_fma_f32 v[70:71], v[146:147], v[70:71], v[150:151]
	s_cbranch_vccz .LBB0_724
	global_store_dwordx4 v[164:165], v[72:75], off
	global_store_dwordx4 v[164:165], v[68:71], off offset:16
